# weight-prep phase: odd workgroups walk their item list in descending order so load and store phases of neighbouring workgroups interleave
# speedup vs baseline: 1.0074x; 1.0074x over previous
.LBB0_17:
	s_or_b64 exec, exec, s[4:5]
	s_load_dwordx4 s[72:75], s[0:1], 0x80
	s_load_dwordx16 s[36:51], s[0:1], 0x0
	s_cmpk_gt_i32 s85, 0x280
	v_mbcnt_lo_u32_b32 v0, -1, 0
	v_mbcnt_hi_u32_b32 v0, -1, v0
	s_waitcnt lgkmcnt(0)
	v_writelane_b32 v254, s36, 16
	s_nop 1
	v_writelane_b32 v254, s37, 17
	v_writelane_b32 v254, s38, 18
	v_writelane_b32 v254, s39, 19
	v_writelane_b32 v254, s40, 20
	v_writelane_b32 v254, s41, 21
	v_writelane_b32 v254, s42, 22
	v_writelane_b32 v254, s43, 23
	v_writelane_b32 v254, s44, 24
	v_writelane_b32 v254, s45, 25
	v_writelane_b32 v254, s46, 26
	v_writelane_b32 v254, s47, 27
	v_writelane_b32 v254, s48, 28
	v_writelane_b32 v254, s49, 29
	v_writelane_b32 v254, s50, 30
	v_writelane_b32 v254, s51, 31
	s_cbranch_scc1 .LBB0_51
	s_add_u32 s6, s28, 0x1e40000
	v_add_u32_e32 v16, s3, v0
	s_addc_u32 s7, s29, 0
	v_and_b32_e32 v0, 15, v0
	s_add_u32 s8, s28, 0x2179000
	v_cvt_f32_ubyte0_e32 v0, v0
	s_addc_u32 s9, s29, 0
	v_mul_f32_e32 v0, 0xbd800000, v0
	s_add_u32 s10, s28, 0x1a00000
	v_mul_f32_e32 v0, 0x41549a78, v0
	s_addc_u32 s11, s29, 0
	v_exp_f32_e32 v17, v0
	s_add_u32 s12, s28, 0x1200000
	s_movk_i32 s0, 0x400
	s_addc_u32 s13, s29, 0
	s_lshl_b32 s4, s16, 2
	s_mov_b32 s56, 0x54442d18
	v_cmp_gt_i32_e64 s[0:1], s0, v16
	s_and_b32 s14, s4, 0xffffff00
	s_movk_i32 s15, 0x1400
	s_movk_i32 s17, 0x3ff
	s_movk_i32 s18, 0xfc00
	v_mov_b32_e32 v1, 0
	s_movk_i32 s19, 0x11ff
	s_mov_b32 s35, 0
	s_movk_i32 s20, 0x3000
	s_movk_i32 s21, 0x6000
	s_mov_b32 s22, 0x9000
	s_mov_b32 s23, 0xc000
	s_mov_b32 s24, 0xf000
	s_mov_b32 s25, 0x12000
	s_mov_b32 s26, 0x15000
	s_movk_i32 s27, 0x500
	s_movk_i32 s33, 0x140
	s_mov_b32 s57, 0x401921fb
	s_mov_b32 s59, 0xc01921fb
	s_movk_i32 s60, 0x1ff
	s_movk_i32 s61, 0xfc
	s_mov_b32 s62, 0x10100
	s_mov_b32 s63, 0x38e38e39
	s_movk_i32 s64, 0x2400
	v_mov_b32_e32 v18, 4
	v_mov_b32_e32 v19, 2
	v_mov_b32_e32 v20, 6
	s_mov_b32 s65, s85
	s_mov_b32 s97, s30
	s_bitcmp1_b32 s85, 0
	s_cbranch_scc0 .Lp0_asc
	s_add_i32 s65, s85, 0x200
	s_cmpk_gt_i32 s65, 0x280
	s_cbranch_scc0 .Lp0_d1
	s_add_i32 s65, s65, 0xffffff00
.Lp0_d1:
	s_sub_i32 s97, 0, s30

.LBB0_19:
	s_add_i32 s65, s65, s97
	s_cmpk_gt_u32 s65, 0x280
	s_cbranch_scc1 .LBB0_51
